# v25: v23 + diff-attn staging stores moved from the iteration tail to behind the 4th QK MFMA of the next iteration (drain under MFMAs), loads one tile further ahead
# speedup vs baseline: 1.0052x; 1.0052x over previous
.LBB0_36:
	s_add_i32 s23, s10, -1
	s_and_b32 s23, s23, 1
	s_sub_i32 s26, s22, 63
	s_cmp_gt_u32 s26, s5
	s_cbranch_scc1 .LBB0_43
	s_mul_i32 s26, s23, 0x7400
	s_add_i32 s26, s26, 0
	s_xor_b32 s78, s23, 1
	s_mulk_i32 s78, 0x7400
	s_cmp_le_u32 s22, s1
	v_add3_u32 v190, s26, v165, v172
	ds_read_b128 v[98:101], v190
	ds_read_b128 v[102:105], v190 offset:32
	ds_read_b128 v[106:109], v190 offset:64
	ds_read_b128 v[110:113], v190 offset:96
	ds_read_b128 v[240:243], v190 offset:4608
	ds_read_b128 v[244:247], v190 offset:4640
	ds_read_b128 v[214:217], v190 offset:4672
	ds_read_b128 v[190:193], v190 offset:4704
	s_setprio 1
	s_waitcnt lgkmcnt(7)
	v_mfma_f32_32x32x16_bf16 v[82:97], v[98:101], v[126:129], v[66:81]
	s_waitcnt lgkmcnt(6)
	v_mfma_f32_32x32x16_bf16 v[82:97], v[102:105], v[130:133], v[82:97]
	s_waitcnt lgkmcnt(5)
	v_mfma_f32_32x32x16_bf16 v[82:97], v[106:109], v[134:137], v[82:97]
	s_waitcnt lgkmcnt(4)
	v_mfma_f32_32x32x16_bf16 v[82:97], v[110:113], v[138:141], v[82:97]
	v_add3_u32 v166, s78, v163, v0
	v_add_u32_e32 v167, s78, v144
	v_add_u32_e32 v168, v167, v164
	v_add_u32_e32 v167, v167, v175
	s_waitcnt vmcnt(2)
	ds_write_b128 v166, v[114:117]
	s_waitcnt vmcnt(1)
	ds_write_b128 v168, v[118:121] offset:9216
	s_waitcnt vmcnt(0)
	ds_write_b128 v167, v[122:125] offset:9216
	s_waitcnt lgkmcnt(6)
	v_mfma_f32_32x32x16_bf16 v[98:113], v[240:243], v[126:129], v[66:81]
	s_waitcnt lgkmcnt(5)
	v_mfma_f32_32x32x16_bf16 v[98:113], v[244:247], v[130:133], v[98:113]
	s_waitcnt lgkmcnt(4)
	v_mfma_f32_32x32x16_bf16 v[98:113], v[214:217], v[134:137], v[98:113]
	s_waitcnt lgkmcnt(3)
	v_mfma_f32_32x32x16_bf16 v[98:113], v[190:193], v[138:141], v[98:113]
	s_setprio 0
	s_cbranch_scc1 .LBB0_39
	v_add_u32_e32 v190, s22, v173
	v_subrev_u32_e32 v191, 63, v190
	v_cmp_le_i32_e32 vcc, v191, v179
	v_subrev_u32_e32 v192, 61, v190
	v_subrev_u32_e32 v190, 60, v190
	s_nop 5
	v_cndmask_b32_e32 v98, v220, v98, vcc
	v_cmp_lt_i32_e32 vcc, v191, v176
	s_nop 1
	v_cndmask_b32_e32 v83, v220, v83, vcc
	v_cmp_le_i32_e32 vcc, v191, v176
	s_nop 1
	v_cndmask_b32_e32 v82, v220, v82, vcc
	v_cmp_le_i32_e32 vcc, v191, v180
	s_nop 1
	v_cndmask_b32_e32 v99, v220, v99, vcc
	v_cmp_le_i32_e32 vcc, v192, v176
	s_nop 1
	v_cndmask_b32_e32 v84, v220, v84, vcc
	v_cmp_le_i32_e32 vcc, v191, v181
	s_nop 1
	v_cndmask_b32_e32 v100, v220, v100, vcc
	v_cmp_le_i32_e32 vcc, v190, v176
	s_nop 1
	v_cndmask_b32_e32 v85, v220, v85, vcc
	v_cmp_le_i32_e32 vcc, v191, v182
	s_nop 1
	v_cndmask_b32_e32 v101, v220, v101, vcc
	v_cmp_le_i32_e32 vcc, v191, v183
	s_nop 1
	v_cndmask_b32_e32 v86, v220, v86, vcc
	v_cmp_le_i32_e32 vcc, v191, v184
	s_nop 1
	v_cndmask_b32_e32 v102, v220, v102, vcc
	v_cmp_le_i32_e32 vcc, v191, v185
	s_nop 1
	v_cndmask_b32_e32 v87, v220, v87, vcc
	v_cmp_le_i32_e32 vcc, v191, v186
	s_nop 1
	v_cndmask_b32_e32 v103, v220, v103, vcc
	v_cmp_le_i32_e32 vcc, v191, v187
	s_nop 1
	v_cndmask_b32_e32 v88, v220, v88, vcc
	v_cmp_le_i32_e32 vcc, v191, v188
	s_nop 1
	v_cndmask_b32_e32 v104, v220, v104, vcc
	v_cmp_le_i32_e32 vcc, v191, v189
	s_nop 1
	v_cndmask_b32_e32 v89, v220, v89, vcc
	v_cmp_le_i32_e32 vcc, v191, v195
	s_nop 1
	v_cndmask_b32_e32 v105, v220, v105, vcc
	v_cmp_le_i32_e32 vcc, v191, v196
	s_nop 1
	v_cndmask_b32_e32 v90, v220, v90, vcc
	v_cmp_le_i32_e32 vcc, v191, v197
	s_nop 1
	v_cndmask_b32_e32 v106, v220, v106, vcc
	v_cmp_le_i32_e32 vcc, v191, v198
	s_nop 1
	v_cndmask_b32_e32 v91, v220, v91, vcc
	v_cmp_le_i32_e32 vcc, v191, v199
	s_nop 1
	v_cndmask_b32_e32 v107, v220, v107, vcc
	v_cmp_le_i32_e32 vcc, v191, v200
	s_nop 1
	v_cndmask_b32_e32 v92, v220, v92, vcc
	v_cmp_le_i32_e32 vcc, v191, v201
	s_nop 1
	v_cndmask_b32_e32 v108, v220, v108, vcc
	v_cmp_le_i32_e32 vcc, v191, v202
	s_nop 1
	v_cndmask_b32_e32 v93, v220, v93, vcc
	v_cmp_le_i32_e32 vcc, v191, v203
	s_nop 1
	v_cndmask_b32_e32 v109, v220, v109, vcc
	v_cmp_le_i32_e32 vcc, v191, v204
	s_nop 1
	v_cndmask_b32_e32 v94, v220, v94, vcc
	v_cmp_le_i32_e32 vcc, v191, v205
	s_nop 1
	v_cndmask_b32_e32 v110, v220, v110, vcc
	v_cmp_le_i32_e32 vcc, v191, v228
	s_nop 1
	v_cndmask_b32_e32 v95, v220, v95, vcc
	v_cmp_le_i32_e32 vcc, v191, v229
	s_nop 1
	v_cndmask_b32_e32 v111, v220, v111, vcc
	v_cmp_le_i32_e32 vcc, v191, v230
	s_nop 1
	v_cndmask_b32_e32 v96, v220, v96, vcc
	v_cmp_le_i32_e32 vcc, v191, v231
	s_nop 1
	v_cndmask_b32_e32 v112, v220, v112, vcc
	v_cmp_le_i32_e32 vcc, v191, v232
	s_nop 1
	v_cndmask_b32_e32 v97, v220, v97, vcc
	v_cmp_le_i32_e32 vcc, v191, v233
	s_nop 1
	v_cndmask_b32_e32 v113, v220, v113, vcc
.LBB0_39:
	s_add_i32 s78, s10, 1
	s_cmp_lt_u32 s78, s4
	s_cbranch_scc0 .Lw_no_c1m
	s_mov_b32 s98, 0x60000
	s_mov_b32 s99, 0
	v_lshl_add_u64 v[240:241], v[160:161], 0, s[50:51]
	v_lshl_add_u64 v[240:241], v[240:241], 0, s[98:99]
	global_load_dwordx4 v[114:117], v[240:241], off
	v_lshl_add_u64 v[242:243], v[148:149], 0, s[50:51]
	v_lshl_add_u64 v[242:243], v[242:243], 0, s[98:99]
	global_load_dwordx4 v[118:121], v[242:243], off
	v_lshl_add_u64 v[240:241], v[146:147], 0, s[50:51]
	v_lshl_add_u64 v[240:241], v[240:241], 0, s[98:99]
	global_load_dwordx4 v[122:125], v[240:241], off
	s_nop 1
	s_branch .Lw_go_c1

.Lw_go_c1:
	v_max3_f32 v240, v82, v83, v84
	v_max3_f32 v241, v98, v99, v100
	v_max3_f32 v242, v90, v91, v92
	v_max3_f32 v243, v106, v107, v108
	v_max3_f32 v240, v240, v85, v86
	v_max3_f32 v241, v241, v101, v102
	v_max3_f32 v242, v242, v93, v94
	v_max3_f32 v243, v243, v109, v110
	v_max3_f32 v240, v240, v87, v88
	v_max3_f32 v241, v241, v103, v104
	v_max3_f32 v242, v242, v95, v96
	v_max3_f32 v243, v243, v111, v112
	v_max3_f32 v240, v240, v89, v105
	v_max3_f32 v242, v242, v97, v113
	v_max3_f32 v240, v240, v241, v242
	v_max_f32_e32 v240, v240, v243
	v_mov_b32_e32 v241, v240
	s_nop 1
	v_permlane32_swap_b32_e32 v240, v241
	v_max_f32_e32 v238, v240, v241
	s_cmp_lg_u32 s79, 0
	s_cbranch_scc1 .Lfo_first_c1
	v_cmp_lt_f32_e32 vcc, 0x41000000, v238
	s_cbranch_vccz .LBB0_44
	v_max_f32_e32 v238, 0, v238
	v_mov_b32_e32 v241, v238
	s_branch .Lfo_resc_c1

.LBB0_43:
	s_xor_b32 s78, s23, 1
	s_mulk_i32 s78, 0x7400
	v_add3_u32 v82, s78, v163, v0
	v_add_u32_e32 v83, s78, v144
	v_add_u32_e32 v84, v83, v164
	v_add_u32_e32 v83, v83, v175
	s_waitcnt vmcnt(2)
	ds_write_b128 v82, v[114:117]
	s_waitcnt vmcnt(1)
	ds_write_b128 v84, v[118:121] offset:9216
	s_waitcnt vmcnt(0)
	ds_write_b128 v83, v[122:125] offset:9216
	s_add_i32 s78, s10, 1
	s_cmp_lt_u32 s78, s4
	s_cbranch_scc0 .Lw_no_c1s
	s_mov_b32 s98, 0x60000
	s_mov_b32 s99, 0
	v_lshl_add_u64 v[240:241], v[160:161], 0, s[50:51]
	v_lshl_add_u64 v[240:241], v[240:241], 0, s[98:99]
	global_load_dwordx4 v[114:117], v[240:241], off
	v_lshl_add_u64 v[242:243], v[148:149], 0, s[50:51]
	v_lshl_add_u64 v[242:243], v[242:243], 0, s[98:99]
	global_load_dwordx4 v[118:121], v[242:243], off
	v_lshl_add_u64 v[240:241], v[146:147], 0, s[50:51]
	v_lshl_add_u64 v[240:241], v[240:241], 0, s[98:99]
	global_load_dwordx4 v[122:125], v[240:241], off
.Lw_no_c1s:
	s_branch .LBB0_47
.LBB0_44:
.LBB0_45:
	v_add3_u32 v190, s26, v178, v177
	ds_read_b64_tr_b16 v[240:241], v190 offset:9216
	ds_read_b64_tr_b16 v[242:243], v190 offset:11776
	ds_read_b64_tr_b16 v[244:245], v190 offset:9280
	ds_read_b64_tr_b16 v[246:247], v190 offset:11840
	ds_read_b64_tr_b16 v[214:215], v190 offset:9344
	ds_read_b64_tr_b16 v[216:217], v190 offset:11904
	v_exp_f32_e32 v82, v82
	v_exp_f32_e32 v83, v83
	v_exp_f32_e32 v84, v84
	v_exp_f32_e32 v85, v85
	v_exp_f32_e32 v86, v86
	v_exp_f32_e32 v87, v87
	v_exp_f32_e32 v88, v88
	v_exp_f32_e32 v89, v89
	v_add_f32_e32 v238, v82, v83
	v_add_f32_e32 v239, v239, v84
	v_add_f32_e32 v238, v238, v85
	v_cvt_pk_bf16_f32 v82, v82, v83
	v_cvt_pk_bf16_f32 v83, v84, v85
	v_cvt_pk_bf16_f32 v84, v86, v87
	v_cvt_pk_bf16_f32 v85, v88, v89
	s_setprio 1
	s_waitcnt lgkmcnt(4)
	v_mfma_f32_32x32x16_bf16 v[2:17], v[82:85], v[240:243], v[2:17]
	v_add_f32_e32 v239, v239, v86
	v_add_f32_e32 v238, v238, v87
	v_add_f32_e32 v239, v239, v88
	v_add_f32_e32 v238, v238, v89
	v_exp_f32_e32 v90, v90
	v_exp_f32_e32 v91, v91
	ds_read_b64_tr_b16 v[240:241], v190 offset:9408
	ds_read_b64_tr_b16 v[242:243], v190 offset:11968
	s_waitcnt lgkmcnt(4)
	v_mfma_f32_32x32x16_bf16 v[50:65], v[82:85], v[244:247], v[50:65]
	v_exp_f32_e32 v92, v92
	v_exp_f32_e32 v93, v93
	v_exp_f32_e32 v94, v94
	ds_read_b64_tr_b16 v[244:245], v190 offset:14336
	ds_read_b64_tr_b16 v[246:247], v190 offset:16896
	s_waitcnt lgkmcnt(4)
	v_mfma_f32_32x32x16_bf16 v[34:49], v[82:85], v[214:217], v[34:49]
	v_exp_f32_e32 v95, v95
	v_exp_f32_e32 v96, v96
	v_exp_f32_e32 v97, v97
	v_add_f32_e32 v239, v239, v90
	ds_read_b64_tr_b16 v[214:215], v190 offset:14400
	ds_read_b64_tr_b16 v[216:217], v190 offset:16960
	s_waitcnt lgkmcnt(4)
	v_mfma_f32_32x32x16_bf16 v[18:33], v[82:85], v[240:243], v[18:33]
	v_add_f32_e32 v238, v238, v91
	v_add_f32_e32 v239, v239, v92
	v_add_f32_e32 v238, v238, v93
	v_cvt_pk_bf16_f32 v90, v90, v91
	v_cvt_pk_bf16_f32 v91, v92, v93
	v_cvt_pk_bf16_f32 v92, v94, v95
	v_cvt_pk_bf16_f32 v93, v96, v97
	s_nop 0
	ds_read_b64_tr_b16 v[240:241], v190 offset:14464
	ds_read_b64_tr_b16 v[242:243], v190 offset:17024
	s_waitcnt lgkmcnt(4)
	v_mfma_f32_32x32x16_bf16 v[2:17], v[90:93], v[244:247], v[2:17]
	v_add_f32_e32 v239, v239, v94
	v_add_f32_e32 v238, v238, v95
	v_add_f32_e32 v239, v239, v96
	v_add_f32_e32 v238, v238, v97
	v_exp_f32_e32 v98, v98
	v_exp_f32_e32 v99, v99
	ds_read_b64_tr_b16 v[244:245], v190 offset:14528
	ds_read_b64_tr_b16 v[246:247], v190 offset:17088
	s_waitcnt lgkmcnt(4)
	v_mfma_f32_32x32x16_bf16 v[50:65], v[90:93], v[214:217], v[50:65]
	v_exp_f32_e32 v100, v100
	v_exp_f32_e32 v101, v101
	v_exp_f32_e32 v102, v102
	ds_read_b64_tr_b16 v[214:215], v190 offset:19456
	ds_read_b64_tr_b16 v[216:217], v190 offset:22016
	s_waitcnt lgkmcnt(4)
	v_mfma_f32_32x32x16_bf16 v[34:49], v[90:93], v[240:243], v[34:49]
	v_exp_f32_e32 v103, v103
	v_exp_f32_e32 v104, v104
	v_exp_f32_e32 v105, v105
	v_add_f32_e32 v239, v239, v98
	ds_read_b64_tr_b16 v[240:241], v190 offset:19520
	ds_read_b64_tr_b16 v[242:243], v190 offset:22080
	s_waitcnt lgkmcnt(4)
	v_mfma_f32_32x32x16_bf16 v[18:33], v[90:93], v[244:247], v[18:33]
	v_add_f32_e32 v238, v238, v99
	v_add_f32_e32 v239, v239, v100
	v_add_f32_e32 v238, v238, v101
	v_cvt_pk_bf16_f32 v98, v98, v99
	v_cvt_pk_bf16_f32 v99, v100, v101
	v_cvt_pk_bf16_f32 v100, v102, v103
	v_cvt_pk_bf16_f32 v101, v104, v105
	s_nop 0
	ds_read_b64_tr_b16 v[244:245], v190 offset:19584
	ds_read_b64_tr_b16 v[246:247], v190 offset:22144
	s_waitcnt lgkmcnt(4)
	v_mfma_f32_32x32x16_bf16 v[2:17], v[98:101], v[214:217], v[2:17]
	v_add_f32_e32 v239, v239, v102
	v_add_f32_e32 v238, v238, v103
	v_add_f32_e32 v239, v239, v104
	v_add_f32_e32 v238, v238, v105
	v_exp_f32_e32 v106, v106
	v_exp_f32_e32 v107, v107
	ds_read_b64_tr_b16 v[214:215], v190 offset:19648
	ds_read_b64_tr_b16 v[216:217], v190 offset:22208
	s_waitcnt lgkmcnt(4)
	v_mfma_f32_32x32x16_bf16 v[50:65], v[98:101], v[240:243], v[50:65]
	v_exp_f32_e32 v108, v108
	v_exp_f32_e32 v109, v109
	v_exp_f32_e32 v110, v110
	ds_read_b64_tr_b16 v[240:241], v190 offset:24576
	ds_read_b64_tr_b16 v[242:243], v190 offset:27136
	s_waitcnt lgkmcnt(4)
	v_mfma_f32_32x32x16_bf16 v[34:49], v[98:101], v[244:247], v[34:49]
	v_exp_f32_e32 v111, v111
	v_exp_f32_e32 v112, v112
	v_exp_f32_e32 v113, v113
	v_add_f32_e32 v239, v239, v106
	ds_read_b64_tr_b16 v[244:245], v190 offset:24640
	ds_read_b64_tr_b16 v[246:247], v190 offset:27200
	s_waitcnt lgkmcnt(4)
	v_mfma_f32_32x32x16_bf16 v[18:33], v[98:101], v[214:217], v[18:33]
	v_add_f32_e32 v238, v238, v107
	v_add_f32_e32 v239, v239, v108
	v_add_f32_e32 v238, v238, v109
	v_cvt_pk_bf16_f32 v106, v106, v107
	v_cvt_pk_bf16_f32 v107, v108, v109
	v_cvt_pk_bf16_f32 v108, v110, v111
	v_cvt_pk_bf16_f32 v109, v112, v113
	s_nop 0
	ds_read_b64_tr_b16 v[214:215], v190 offset:24704
	ds_read_b64_tr_b16 v[216:217], v190 offset:27264
	s_waitcnt lgkmcnt(4)
	v_mfma_f32_32x32x16_bf16 v[2:17], v[106:109], v[240:243], v[2:17]
	v_add_f32_e32 v239, v239, v110
	v_add_f32_e32 v238, v238, v111
	v_add_f32_e32 v239, v239, v112
	v_add_f32_e32 v238, v238, v113
	v_add_f32_e32 v239, v239, v238
	ds_read_b64_tr_b16 v[240:241], v190 offset:24768
	ds_read_b64_tr_b16 v[242:243], v190 offset:27328
	s_waitcnt lgkmcnt(4)
	v_mfma_f32_32x32x16_bf16 v[50:65], v[106:109], v[244:247], v[50:65]
	s_waitcnt lgkmcnt(2)
	v_mfma_f32_32x32x16_bf16 v[34:49], v[106:109], v[214:217], v[34:49]
	s_waitcnt lgkmcnt(0)
	v_mfma_f32_32x32x16_bf16 v[18:33], v[106:109], v[240:243], v[18:33]
	s_setprio 0
	s_movk_i32 s77, 0x110
.LBB0_47:
	s_add_i32 s22, s22, 64
	s_add_u32 s50, s50, 0x60000
	s_addc_u32 s51, s51, 0
	s_add_i32 s10, s10, 1
	s_mul_i32 s23, s4, 0x60000
	s_cmp_lg_u32 s23, s50
	s_waitcnt lgkmcnt(0)
	s_barrier
	s_cbranch_scc0 .Lfo_out_c1
	s_cmp_lt_u32 s10, s4
	s_cselect_b64 s[60:61], -1, 0
	s_branch .LBB0_36

.LBB0_51:
	s_add_i32 s23, s22, -1
	s_and_b32 s23, s23, 1
	s_sub_i32 s26, s10, 63
	s_cmp_gt_u32 s26, s5
	s_cbranch_scc1 .LBB0_58
	s_mul_i32 s26, s23, 0x7400
	s_add_i32 s26, s26, 0
	s_xor_b32 s78, s23, 1
	s_mulk_i32 s78, 0x7400
	s_cmp_le_u32 s10, s1
	v_add3_u32 v152, s26, v165, v172
	ds_read_b128 v[98:101], v152
	ds_read_b128 v[102:105], v152 offset:32
	ds_read_b128 v[106:109], v152 offset:64
	ds_read_b128 v[110:113], v152 offset:96
	ds_read_b128 v[154:157], v152 offset:4608
	ds_read_b128 v[190:193], v152 offset:4640
	ds_read_b128 v[214:217], v152 offset:4672
	ds_read_b128 v[234:237], v152 offset:4704
	s_setprio 1
	s_waitcnt lgkmcnt(7)
	v_mfma_f32_32x32x16_bf16 v[82:97], v[98:101], v[114:117], v[66:81]
	s_waitcnt lgkmcnt(6)
	v_mfma_f32_32x32x16_bf16 v[82:97], v[102:105], v[118:121], v[82:97]
	s_waitcnt lgkmcnt(5)
	v_mfma_f32_32x32x16_bf16 v[82:97], v[106:109], v[126:129], v[82:97]
	s_waitcnt lgkmcnt(4)
	v_mfma_f32_32x32x16_bf16 v[82:97], v[110:113], v[130:133], v[82:97]
	v_add3_u32 v166, s78, v163, v0
	v_add_u32_e32 v167, s78, v144
	v_add_u32_e32 v168, v167, v164
	v_add_u32_e32 v167, v167, v175
	s_waitcnt vmcnt(2)
	ds_write_b128 v166, v[122:125]
	s_waitcnt vmcnt(1)
	ds_write_b128 v168, v[134:137] offset:9216
	s_waitcnt vmcnt(0)
	ds_write_b128 v167, v[138:141] offset:9216
	s_waitcnt lgkmcnt(6)
	v_mfma_f32_32x32x16_bf16 v[98:113], v[154:157], v[114:117], v[66:81]
	s_waitcnt lgkmcnt(5)
	v_mfma_f32_32x32x16_bf16 v[98:113], v[190:193], v[118:121], v[98:113]
	s_waitcnt lgkmcnt(4)
	v_mfma_f32_32x32x16_bf16 v[98:113], v[214:217], v[126:129], v[98:113]
	s_waitcnt lgkmcnt(3)
	v_mfma_f32_32x32x16_bf16 v[98:113], v[234:237], v[130:133], v[98:113]
	s_setprio 0
	s_cbranch_scc1 .LBB0_54
	v_add_u32_e32 v152, s10, v173
	v_subrev_u32_e32 v154, 63, v152
	v_cmp_le_i32_e32 vcc, v154, v179
	v_subrev_u32_e32 v155, 61, v152
	v_subrev_u32_e32 v152, 60, v152
	s_nop 5
	v_cndmask_b32_e32 v98, v220, v98, vcc
	v_cmp_lt_i32_e32 vcc, v154, v176
	s_nop 1
	v_cndmask_b32_e32 v83, v220, v83, vcc
	v_cmp_le_i32_e32 vcc, v154, v176
	s_nop 1
	v_cndmask_b32_e32 v82, v220, v82, vcc
	v_cmp_le_i32_e32 vcc, v154, v180
	s_nop 1
	v_cndmask_b32_e32 v99, v220, v99, vcc
	v_cmp_le_i32_e32 vcc, v155, v176
	s_nop 1
	v_cndmask_b32_e32 v84, v220, v84, vcc
	v_cmp_le_i32_e32 vcc, v154, v181
	s_nop 1
	v_cndmask_b32_e32 v100, v220, v100, vcc
	v_cmp_le_i32_e32 vcc, v152, v176
	s_nop 1
	v_cndmask_b32_e32 v85, v220, v85, vcc
	v_cmp_le_i32_e32 vcc, v154, v182
	s_nop 1
	v_cndmask_b32_e32 v101, v220, v101, vcc
	v_cmp_le_i32_e32 vcc, v154, v183
	s_nop 1
	v_cndmask_b32_e32 v86, v220, v86, vcc
	v_cmp_le_i32_e32 vcc, v154, v184
	s_nop 1
	v_cndmask_b32_e32 v102, v220, v102, vcc
	v_cmp_le_i32_e32 vcc, v154, v185
	s_nop 1
	v_cndmask_b32_e32 v87, v220, v87, vcc
	v_cmp_le_i32_e32 vcc, v154, v186
	s_nop 1
	v_cndmask_b32_e32 v103, v220, v103, vcc
	v_cmp_le_i32_e32 vcc, v154, v187
	s_nop 1
	v_cndmask_b32_e32 v88, v220, v88, vcc
	v_cmp_le_i32_e32 vcc, v154, v188
	s_nop 1
	v_cndmask_b32_e32 v104, v220, v104, vcc
	v_cmp_le_i32_e32 vcc, v154, v189
	s_nop 1
	v_cndmask_b32_e32 v89, v220, v89, vcc
	v_cmp_le_i32_e32 vcc, v154, v195
	s_nop 1
	v_cndmask_b32_e32 v105, v220, v105, vcc
	v_cmp_le_i32_e32 vcc, v154, v196
	s_nop 1
	v_cndmask_b32_e32 v90, v220, v90, vcc
	v_cmp_le_i32_e32 vcc, v154, v197
	s_nop 1
	v_cndmask_b32_e32 v106, v220, v106, vcc
	v_cmp_le_i32_e32 vcc, v154, v198
	s_nop 1
	v_cndmask_b32_e32 v91, v220, v91, vcc
	v_cmp_le_i32_e32 vcc, v154, v199
	s_nop 1
	v_cndmask_b32_e32 v107, v220, v107, vcc
	v_cmp_le_i32_e32 vcc, v154, v200
	s_nop 1
	v_cndmask_b32_e32 v92, v220, v92, vcc
	v_cmp_le_i32_e32 vcc, v154, v201
	s_nop 1
	v_cndmask_b32_e32 v108, v220, v108, vcc
	v_cmp_le_i32_e32 vcc, v154, v202
	s_nop 1
	v_cndmask_b32_e32 v93, v220, v93, vcc
	v_cmp_le_i32_e32 vcc, v154, v203
	s_nop 1
	v_cndmask_b32_e32 v109, v220, v109, vcc
	v_cmp_le_i32_e32 vcc, v154, v204
	s_nop 1
	v_cndmask_b32_e32 v94, v220, v94, vcc
	v_cmp_le_i32_e32 vcc, v154, v205
	s_nop 1
	v_cndmask_b32_e32 v110, v220, v110, vcc
	v_cmp_le_i32_e32 vcc, v154, v228
	s_nop 1
	v_cndmask_b32_e32 v95, v220, v95, vcc
	v_cmp_le_i32_e32 vcc, v154, v229
	s_nop 1
	v_cndmask_b32_e32 v111, v220, v111, vcc
	v_cmp_le_i32_e32 vcc, v154, v230
	s_nop 1
	v_cndmask_b32_e32 v96, v220, v96, vcc
	v_cmp_le_i32_e32 vcc, v154, v231
	s_nop 1
	v_cndmask_b32_e32 v112, v220, v112, vcc
	v_cmp_le_i32_e32 vcc, v154, v232
	s_nop 1
	v_cndmask_b32_e32 v97, v220, v97, vcc
	v_cmp_le_i32_e32 vcc, v154, v233
	s_nop 1
	v_cndmask_b32_e32 v113, v220, v113, vcc
.LBB0_54:
	s_add_i32 s78, s22, 1
	s_cmp_lt_u32 s78, s4
	s_cbranch_scc0 .Lw_no_c2m
	s_mov_b32 s98, 0x60000
	s_mov_b32 s99, 0
	v_lshl_add_u64 v[154:155], v[150:151], 0, s[60:61]
	v_lshl_add_u64 v[154:155], v[154:155], 0, s[98:99]
	global_load_dwordx4 v[122:125], v[154:155], off
	v_lshl_add_u64 v[156:157], v[148:149], 0, s[60:61]
	v_lshl_add_u64 v[156:157], v[156:157], 0, s[98:99]
	global_load_dwordx4 v[134:137], v[156:157], off
	v_lshl_add_u64 v[154:155], v[146:147], 0, s[60:61]
	v_lshl_add_u64 v[154:155], v[154:155], 0, s[98:99]
	global_load_dwordx4 v[138:141], v[154:155], off
	s_nop 1
	s_branch .Lw_go_c2

.Lw_go_c2:
	v_max3_f32 v154, v82, v83, v84
	v_max3_f32 v155, v98, v99, v100
	v_max3_f32 v156, v90, v91, v92
	v_max3_f32 v157, v106, v107, v108
	v_max3_f32 v154, v154, v85, v86
	v_max3_f32 v155, v155, v101, v102
	v_max3_f32 v156, v156, v93, v94
	v_max3_f32 v157, v157, v109, v110
	v_max3_f32 v154, v154, v87, v88
	v_max3_f32 v155, v155, v103, v104
	v_max3_f32 v156, v156, v95, v96
	v_max3_f32 v157, v157, v111, v112
	v_max3_f32 v154, v154, v89, v105
	v_max3_f32 v156, v156, v97, v113
	v_max3_f32 v154, v154, v155, v156
	v_max_f32_e32 v154, v154, v157
	v_mov_b32_e32 v155, v154
	s_nop 1
	v_permlane32_swap_b32_e32 v154, v155
	v_max_f32_e32 v152, v154, v155
	s_cmp_lg_u32 s79, 0
	s_cbranch_scc1 .Lfo_first_c2
	v_cmp_lt_f32_e32 vcc, 0x41000000, v152
	s_cbranch_vccz .LBB0_59
	v_max_f32_e32 v152, 0, v152
	v_mov_b32_e32 v155, v152
	s_branch .Lfo_resc_c2

.LBB0_58:
	s_xor_b32 s78, s23, 1
	s_mulk_i32 s78, 0x7400
	v_add3_u32 v82, s78, v163, v0
	v_add_u32_e32 v83, s78, v144
	v_add_u32_e32 v84, v83, v164
	v_add_u32_e32 v83, v83, v175
	s_waitcnt vmcnt(2)
	ds_write_b128 v82, v[122:125]
	s_waitcnt vmcnt(1)
	ds_write_b128 v84, v[134:137] offset:9216
	s_waitcnt vmcnt(0)
	ds_write_b128 v83, v[138:141] offset:9216
	s_add_i32 s78, s22, 1
	s_cmp_lt_u32 s78, s4
	s_cbranch_scc0 .Lw_no_c2s
	s_mov_b32 s98, 0x60000
	s_mov_b32 s99, 0
	v_lshl_add_u64 v[154:155], v[150:151], 0, s[60:61]
	v_lshl_add_u64 v[154:155], v[154:155], 0, s[98:99]
	global_load_dwordx4 v[122:125], v[154:155], off
	v_lshl_add_u64 v[156:157], v[148:149], 0, s[60:61]
	v_lshl_add_u64 v[156:157], v[156:157], 0, s[98:99]
	global_load_dwordx4 v[134:137], v[156:157], off
	v_lshl_add_u64 v[154:155], v[146:147], 0, s[60:61]
	v_lshl_add_u64 v[154:155], v[154:155], 0, s[98:99]
	global_load_dwordx4 v[138:141], v[154:155], off
.Lw_no_c2s:
	s_branch .LBB0_62
.LBB0_59:
.LBB0_60:
	v_add3_u32 v153, s26, v178, v177
	ds_read_b64_tr_b16 v[154:155], v153 offset:9216
	ds_read_b64_tr_b16 v[156:157], v153 offset:11776
	ds_read_b64_tr_b16 v[190:191], v153 offset:9280
	ds_read_b64_tr_b16 v[192:193], v153 offset:11840
	ds_read_b64_tr_b16 v[214:215], v153 offset:9344
	ds_read_b64_tr_b16 v[216:217], v153 offset:11904
	ds_read_b64_tr_b16 v[234:235], v153 offset:9408
	ds_read_b64_tr_b16 v[236:237], v153 offset:11968
	v_exp_f32_e32 v82, v82
	v_exp_f32_e32 v83, v83
	v_exp_f32_e32 v84, v84
	v_exp_f32_e32 v85, v85
	v_exp_f32_e32 v86, v86
	v_exp_f32_e32 v87, v87
	v_exp_f32_e32 v88, v88
	v_exp_f32_e32 v89, v89
	v_add_f32_e32 v239, v82, v83
	v_add_f32_e32 v238, v238, v84
	v_add_f32_e32 v239, v239, v85
	v_cvt_pk_bf16_f32 v82, v82, v83
	v_cvt_pk_bf16_f32 v83, v84, v85
	v_cvt_pk_bf16_f32 v84, v86, v87
	v_cvt_pk_bf16_f32 v85, v88, v89
	s_setprio 1
	s_waitcnt lgkmcnt(6)
	v_mfma_f32_32x32x16_bf16 v[2:17], v[82:85], v[154:157], v[2:17]
	v_add_f32_e32 v238, v238, v86
	v_add_f32_e32 v239, v239, v87
	v_add_f32_e32 v238, v238, v88
	v_add_f32_e32 v239, v239, v89
	v_exp_f32_e32 v90, v90
	v_exp_f32_e32 v91, v91
	ds_read_b64_tr_b16 v[154:155], v153 offset:14336
	ds_read_b64_tr_b16 v[156:157], v153 offset:16896
	s_waitcnt lgkmcnt(6)
	v_mfma_f32_32x32x16_bf16 v[50:65], v[82:85], v[190:193], v[50:65]
	v_exp_f32_e32 v92, v92
	v_exp_f32_e32 v93, v93
	v_exp_f32_e32 v94, v94
	ds_read_b64_tr_b16 v[190:191], v153 offset:14400
	ds_read_b64_tr_b16 v[192:193], v153 offset:16960
	s_waitcnt lgkmcnt(6)
	v_mfma_f32_32x32x16_bf16 v[18:33], v[82:85], v[214:217], v[18:33]
	v_exp_f32_e32 v95, v95
	v_exp_f32_e32 v96, v96
	v_exp_f32_e32 v97, v97
	v_add_f32_e32 v238, v238, v90
	ds_read_b64_tr_b16 v[214:215], v153 offset:14464
	ds_read_b64_tr_b16 v[216:217], v153 offset:17024
	s_waitcnt lgkmcnt(6)
	v_mfma_f32_32x32x16_bf16 v[34:49], v[82:85], v[234:237], v[34:49]
	v_add_f32_e32 v239, v239, v91
	v_add_f32_e32 v238, v238, v92
	v_add_f32_e32 v239, v239, v93
	v_cvt_pk_bf16_f32 v90, v90, v91
	v_cvt_pk_bf16_f32 v91, v92, v93
	v_cvt_pk_bf16_f32 v92, v94, v95
	v_cvt_pk_bf16_f32 v93, v96, v97
	s_nop 0
	ds_read_b64_tr_b16 v[234:235], v153 offset:14528
	ds_read_b64_tr_b16 v[236:237], v153 offset:17088
	s_waitcnt lgkmcnt(6)
	v_mfma_f32_32x32x16_bf16 v[2:17], v[90:93], v[154:157], v[2:17]
	v_add_f32_e32 v238, v238, v94
	v_add_f32_e32 v239, v239, v95
	v_add_f32_e32 v238, v238, v96
	v_add_f32_e32 v239, v239, v97
	v_exp_f32_e32 v98, v98
	v_exp_f32_e32 v99, v99
	ds_read_b64_tr_b16 v[154:155], v153 offset:19456
	ds_read_b64_tr_b16 v[156:157], v153 offset:22016
	s_waitcnt lgkmcnt(6)
	v_mfma_f32_32x32x16_bf16 v[50:65], v[90:93], v[190:193], v[50:65]
	v_exp_f32_e32 v100, v100
	v_exp_f32_e32 v101, v101
	v_exp_f32_e32 v102, v102
	ds_read_b64_tr_b16 v[190:191], v153 offset:19520
	ds_read_b64_tr_b16 v[192:193], v153 offset:22080
	s_waitcnt lgkmcnt(6)
	v_mfma_f32_32x32x16_bf16 v[18:33], v[90:93], v[214:217], v[18:33]
	v_exp_f32_e32 v103, v103
	v_exp_f32_e32 v104, v104
	v_exp_f32_e32 v105, v105
	v_add_f32_e32 v238, v238, v98
	ds_read_b64_tr_b16 v[214:215], v153 offset:19584
	ds_read_b64_tr_b16 v[216:217], v153 offset:22144
	s_waitcnt lgkmcnt(6)
	v_mfma_f32_32x32x16_bf16 v[34:49], v[90:93], v[234:237], v[34:49]
	v_add_f32_e32 v239, v239, v99
	v_add_f32_e32 v238, v238, v100
	v_add_f32_e32 v239, v239, v101
	v_cvt_pk_bf16_f32 v98, v98, v99
	v_cvt_pk_bf16_f32 v99, v100, v101
	v_cvt_pk_bf16_f32 v100, v102, v103
	v_cvt_pk_bf16_f32 v101, v104, v105
	s_nop 0
	ds_read_b64_tr_b16 v[234:235], v153 offset:19648
	ds_read_b64_tr_b16 v[236:237], v153 offset:22208
	s_waitcnt lgkmcnt(6)
	v_mfma_f32_32x32x16_bf16 v[2:17], v[98:101], v[154:157], v[2:17]
	v_add_f32_e32 v238, v238, v102
	v_add_f32_e32 v239, v239, v103
	v_add_f32_e32 v238, v238, v104
	v_add_f32_e32 v239, v239, v105
	v_exp_f32_e32 v106, v106
	v_exp_f32_e32 v107, v107
	ds_read_b64_tr_b16 v[154:155], v153 offset:24576
	ds_read_b64_tr_b16 v[156:157], v153 offset:27136
	s_waitcnt lgkmcnt(6)
	v_mfma_f32_32x32x16_bf16 v[50:65], v[98:101], v[190:193], v[50:65]
	v_exp_f32_e32 v108, v108
	v_exp_f32_e32 v109, v109
	v_exp_f32_e32 v110, v110
	ds_read_b64_tr_b16 v[190:191], v153 offset:24640
	ds_read_b64_tr_b16 v[192:193], v153 offset:27200
	s_waitcnt lgkmcnt(6)
	v_mfma_f32_32x32x16_bf16 v[18:33], v[98:101], v[214:217], v[18:33]
	v_exp_f32_e32 v111, v111
	v_exp_f32_e32 v112, v112
	v_exp_f32_e32 v113, v113
	v_add_f32_e32 v238, v238, v106
	ds_read_b64_tr_b16 v[214:215], v153 offset:24704
	ds_read_b64_tr_b16 v[216:217], v153 offset:27264
	s_waitcnt lgkmcnt(6)
	v_mfma_f32_32x32x16_bf16 v[34:49], v[98:101], v[234:237], v[34:49]
	v_add_f32_e32 v239, v239, v107
	v_add_f32_e32 v238, v238, v108
	v_add_f32_e32 v239, v239, v109
	v_cvt_pk_bf16_f32 v106, v106, v107
	v_cvt_pk_bf16_f32 v107, v108, v109
	v_cvt_pk_bf16_f32 v108, v110, v111
	v_cvt_pk_bf16_f32 v109, v112, v113
	s_nop 0
	ds_read_b64_tr_b16 v[234:235], v153 offset:24768
	ds_read_b64_tr_b16 v[236:237], v153 offset:27328
	s_waitcnt lgkmcnt(6)
	v_mfma_f32_32x32x16_bf16 v[2:17], v[106:109], v[154:157], v[2:17]
	v_add_f32_e32 v238, v238, v110
	v_add_f32_e32 v239, v239, v111
	v_add_f32_e32 v238, v238, v112
	v_add_f32_e32 v239, v239, v113
	v_add_f32_e32 v238, v238, v239
	s_waitcnt lgkmcnt(4)
	v_mfma_f32_32x32x16_bf16 v[50:65], v[106:109], v[190:193], v[50:65]
	s_waitcnt lgkmcnt(2)
	v_mfma_f32_32x32x16_bf16 v[18:33], v[106:109], v[214:217], v[18:33]
	s_waitcnt lgkmcnt(0)
	v_mfma_f32_32x32x16_bf16 v[34:49], v[106:109], v[234:237], v[34:49]
	s_setprio 0
	s_movk_i32 s77, 0x110
.LBB0_62:
	s_add_i32 s10, s10, 64
	s_add_u32 s60, s60, 0x60000
	s_addc_u32 s61, s61, 0
	s_add_i32 s22, s22, 1
	s_cmp_lg_u32 s50, s60
	s_waitcnt lgkmcnt(0)
	s_barrier
	s_cbranch_scc0 .Lfo_out_c2
	s_cmp_lt_u32 s22, s4
	s_cselect_b64 s[62:63], -1, 0
	s_branch .LBB0_51

.LBB0_66:
	s_add_i32 s23, s4, -1
	s_and_b32 s23, s23, 1
	s_cmp_gt_u32 s22, s11
	s_cbranch_scc1 .LBB0_73
	s_mul_i32 s26, s23, 0x7400
	s_add_i32 s26, s26, 0
	s_add_i32 s30, s22, 63
	s_xor_b32 s78, s23, 1
	s_mulk_i32 s78, 0x7400
	s_cmp_le_u32 s30, s1
	v_add3_u32 v206, s26, v177, v178
	ds_read_b128 v[98:101], v206
	ds_read_b128 v[102:105], v206 offset:32
	ds_read_b128 v[106:109], v206 offset:64
	ds_read_b128 v[110:113], v206 offset:96
	ds_read_b128 v[190:193], v206 offset:4608
	ds_read_b128 v[214:217], v206 offset:4640
	ds_read_b128 v[244:247], v206 offset:4672
	ds_read_b128 v[206:209], v206 offset:4704
	s_setprio 1
	s_waitcnt lgkmcnt(7)
	v_mfma_f32_32x32x16_bf16 v[82:97], v[98:101], v[126:129], v[66:81]
	s_waitcnt lgkmcnt(6)
	v_mfma_f32_32x32x16_bf16 v[82:97], v[102:105], v[130:133], v[82:97]
	s_waitcnt lgkmcnt(5)
	v_mfma_f32_32x32x16_bf16 v[82:97], v[106:109], v[134:137], v[82:97]
	s_waitcnt lgkmcnt(4)
	v_mfma_f32_32x32x16_bf16 v[82:97], v[110:113], v[138:141], v[82:97]
	v_add3_u32 v166, s78, v174, v0
	v_add_u32_e32 v167, s78, v144
	v_add_u32_e32 v168, v167, v175
	v_add_u32_e32 v167, v167, v176
	s_waitcnt vmcnt(2)
	ds_write_b128 v166, v[114:117]
	s_waitcnt vmcnt(1)
	ds_write_b128 v168, v[118:121] offset:9216
	s_waitcnt vmcnt(0)
	ds_write_b128 v167, v[122:125] offset:9216
	s_waitcnt lgkmcnt(6)
	v_mfma_f32_32x32x16_bf16 v[98:113], v[190:193], v[126:129], v[66:81]
	s_waitcnt lgkmcnt(5)
	v_mfma_f32_32x32x16_bf16 v[98:113], v[214:217], v[130:133], v[98:113]
	s_waitcnt lgkmcnt(4)
	v_mfma_f32_32x32x16_bf16 v[98:113], v[244:247], v[134:137], v[98:113]
	s_waitcnt lgkmcnt(3)
	v_mfma_f32_32x32x16_bf16 v[98:113], v[206:209], v[138:141], v[98:113]
	s_setprio 0
	s_cbranch_scc1 .LBB0_69
	v_add_u32_e32 v190, s22, v179
	v_cmp_le_i32_e32 vcc, v190, v183
	v_add_u32_e32 v191, 2, v190
	s_nop 7
	v_cndmask_b32_e32 v98, v220, v98, vcc
	v_cmp_lt_i32_e32 vcc, v190, v173
	s_nop 1
	v_cndmask_b32_e32 v83, v220, v83, vcc
	v_cmp_le_i32_e32 vcc, v190, v173
	s_nop 1
	v_cndmask_b32_e32 v82, v220, v82, vcc
	v_cmp_le_i32_e32 vcc, v190, v184
	s_nop 1
	v_cndmask_b32_e32 v99, v220, v99, vcc
	v_cmp_le_i32_e32 vcc, v191, v173
	v_add_u32_e32 v191, 3, v190
	s_nop 0
	v_cndmask_b32_e32 v84, v220, v84, vcc
	v_cmp_le_i32_e32 vcc, v190, v185
	s_nop 1
	v_cndmask_b32_e32 v100, v220, v100, vcc
	v_cmp_le_i32_e32 vcc, v191, v173
	s_nop 1
	v_cndmask_b32_e32 v85, v220, v85, vcc
	v_cmp_le_i32_e32 vcc, v190, v186
	s_nop 1
	v_cndmask_b32_e32 v101, v220, v101, vcc
	v_cmp_le_i32_e32 vcc, v190, v187
	s_nop 1
	v_cndmask_b32_e32 v86, v220, v86, vcc
	v_cmp_le_i32_e32 vcc, v190, v188
	s_nop 1
	v_cndmask_b32_e32 v102, v220, v102, vcc
	v_cmp_le_i32_e32 vcc, v190, v189
	s_nop 1
	v_cndmask_b32_e32 v87, v220, v87, vcc
	v_cmp_le_i32_e32 vcc, v190, v195
	s_nop 1
	v_cndmask_b32_e32 v103, v220, v103, vcc
	v_cmp_le_i32_e32 vcc, v190, v196
	s_nop 1
	v_cndmask_b32_e32 v88, v220, v88, vcc
	v_cmp_le_i32_e32 vcc, v190, v197
	s_nop 1
	v_cndmask_b32_e32 v104, v220, v104, vcc
	v_cmp_le_i32_e32 vcc, v190, v198
	s_nop 1
	v_cndmask_b32_e32 v89, v220, v89, vcc
	v_cmp_le_i32_e32 vcc, v190, v199
	s_nop 1
	v_cndmask_b32_e32 v105, v220, v105, vcc
	v_cmp_le_i32_e32 vcc, v190, v200
	s_nop 1
	v_cndmask_b32_e32 v90, v220, v90, vcc
	v_cmp_le_i32_e32 vcc, v190, v201
	s_nop 1
	v_cndmask_b32_e32 v106, v220, v106, vcc
	v_cmp_le_i32_e32 vcc, v190, v202
	s_nop 1
	v_cndmask_b32_e32 v91, v220, v91, vcc
	v_cmp_le_i32_e32 vcc, v190, v203
	s_nop 1
	v_cndmask_b32_e32 v107, v220, v107, vcc
	v_cmp_le_i32_e32 vcc, v190, v204
	s_nop 1
	v_cndmask_b32_e32 v92, v220, v92, vcc
	v_cmp_le_i32_e32 vcc, v190, v205
	s_nop 1
	v_cndmask_b32_e32 v108, v220, v108, vcc
	v_cmp_le_i32_e32 vcc, v190, v228
	s_nop 1
	v_cndmask_b32_e32 v93, v220, v93, vcc
	v_cmp_le_i32_e32 vcc, v190, v229
	s_nop 1
	v_cndmask_b32_e32 v109, v220, v109, vcc
	v_cmp_le_i32_e32 vcc, v190, v230
	s_nop 1
	v_cndmask_b32_e32 v94, v220, v94, vcc
	v_cmp_le_i32_e32 vcc, v190, v231
	s_nop 1
	v_cndmask_b32_e32 v110, v220, v110, vcc
	v_cmp_le_i32_e32 vcc, v190, v232
	s_nop 1
	v_cndmask_b32_e32 v95, v220, v95, vcc
	v_cmp_le_i32_e32 vcc, v190, v233
	s_nop 1
	v_cndmask_b32_e32 v111, v220, v111, vcc
	v_cmp_le_i32_e32 vcc, v190, v234
	s_nop 1
	v_cndmask_b32_e32 v96, v220, v96, vcc
	v_cmp_le_i32_e32 vcc, v190, v235
	s_nop 1
	v_cndmask_b32_e32 v112, v220, v112, vcc
	v_cmp_le_i32_e32 vcc, v190, v236
	s_nop 1
	v_cndmask_b32_e32 v97, v220, v97, vcc
	v_cmp_le_i32_e32 vcc, v190, v237
	s_nop 1
	v_cndmask_b32_e32 v113, v220, v113, vcc
.LBB0_69:
	s_add_i32 s78, s4, 1
	s_cmp_lt_u32 s78, s5
	s_cbranch_scc0 .Lw_no_c3m
	s_mov_b32 s98, 0x60000
	s_mov_b32 s99, 0
	v_lshl_add_u64 v[190:191], v[160:161], 0, s[36:37]
	v_lshl_add_u64 v[190:191], v[190:191], 0, s[98:99]
	global_load_dwordx4 v[114:117], v[190:191], off
	v_lshl_add_u64 v[192:193], v[162:163], 0, s[36:37]
	v_lshl_add_u64 v[192:193], v[192:193], 0, s[98:99]
	global_load_dwordx4 v[118:121], v[192:193], off
	v_lshl_add_u64 v[190:191], v[164:165], 0, s[36:37]
	v_lshl_add_u64 v[190:191], v[190:191], 0, s[98:99]
	global_load_dwordx4 v[122:125], v[190:191], off
	s_nop 1
	s_branch .Lw_go_c3

.Lw_go_c3:
	v_max3_f32 v190, v82, v83, v84
	v_max3_f32 v191, v98, v99, v100
	v_max3_f32 v192, v90, v91, v92
	v_max3_f32 v193, v106, v107, v108
	v_max3_f32 v190, v190, v85, v86
	v_max3_f32 v191, v191, v101, v102
	v_max3_f32 v192, v192, v93, v94
	v_max3_f32 v193, v193, v109, v110
	v_max3_f32 v190, v190, v87, v88
	v_max3_f32 v191, v191, v103, v104
	v_max3_f32 v192, v192, v95, v96
	v_max3_f32 v193, v193, v111, v112
	v_max3_f32 v190, v190, v89, v105
	v_max3_f32 v192, v192, v97, v113
	v_max3_f32 v190, v190, v191, v192
	v_max_f32_e32 v190, v190, v193
	v_mov_b32_e32 v191, v190
	s_nop 1
	v_permlane32_swap_b32_e32 v190, v191
	v_max_f32_e32 v242, v190, v191
	s_cmp_lg_u32 s79, 0
	s_cbranch_scc1 .Lfo_first_c3
	v_cmp_lt_f32_e32 vcc, 0x41000000, v242
	s_cbranch_vccz .LBB0_74
	v_max_f32_e32 v242, 0, v242
	v_mov_b32_e32 v191, v242
	s_branch .Lfo_resc_c3

.LBB0_73:
	s_xor_b32 s78, s23, 1
	s_mulk_i32 s78, 0x7400
	v_add3_u32 v82, s78, v174, v0
	v_add_u32_e32 v83, s78, v144
	v_add_u32_e32 v84, v83, v175
	v_add_u32_e32 v83, v83, v176
	s_waitcnt vmcnt(2)
	ds_write_b128 v82, v[114:117]
	s_waitcnt vmcnt(1)
	ds_write_b128 v84, v[118:121] offset:9216
	s_waitcnt vmcnt(0)
	ds_write_b128 v83, v[122:125] offset:9216
	s_add_i32 s78, s4, 1
	s_cmp_lt_u32 s78, s5
	s_cbranch_scc0 .Lw_no_c3s
	s_mov_b32 s98, 0x60000
	s_mov_b32 s99, 0
	v_lshl_add_u64 v[190:191], v[160:161], 0, s[36:37]
	v_lshl_add_u64 v[190:191], v[190:191], 0, s[98:99]
	global_load_dwordx4 v[114:117], v[190:191], off
	v_lshl_add_u64 v[192:193], v[162:163], 0, s[36:37]
	v_lshl_add_u64 v[192:193], v[192:193], 0, s[98:99]
	global_load_dwordx4 v[118:121], v[192:193], off
	v_lshl_add_u64 v[190:191], v[164:165], 0, s[36:37]
	v_lshl_add_u64 v[190:191], v[190:191], 0, s[98:99]
	global_load_dwordx4 v[122:125], v[190:191], off
.Lw_no_c3s:
	s_branch .LBB0_77
.LBB0_74:
.LBB0_75:
	v_add3_u32 v190, s26, v182, v181
	ds_read_b64_tr_b16 v[214:215], v190 offset:9216
	ds_read_b64_tr_b16 v[216:217], v190 offset:11776
	ds_read_b64_tr_b16 v[244:245], v190 offset:9280
	ds_read_b64_tr_b16 v[246:247], v190 offset:11840
	ds_read_b64_tr_b16 v[206:207], v190 offset:9344
	ds_read_b64_tr_b16 v[208:209], v190 offset:11904
	v_exp_f32_e32 v82, v82
	v_exp_f32_e32 v83, v83
	v_exp_f32_e32 v84, v84
	v_exp_f32_e32 v85, v85
	v_exp_f32_e32 v86, v86
	v_exp_f32_e32 v87, v87
	v_exp_f32_e32 v88, v88
	v_exp_f32_e32 v89, v89
	v_add_f32_e32 v242, v82, v83
	v_add_f32_e32 v243, v243, v84
	v_add_f32_e32 v242, v242, v85
	v_cvt_pk_bf16_f32 v82, v82, v83
	v_cvt_pk_bf16_f32 v83, v84, v85
	v_cvt_pk_bf16_f32 v84, v86, v87
	v_cvt_pk_bf16_f32 v85, v88, v89
	s_setprio 1
	s_waitcnt lgkmcnt(4)
	v_mfma_f32_32x32x16_bf16 v[2:17], v[82:85], v[214:217], v[2:17]
	v_add_f32_e32 v243, v243, v86
	v_add_f32_e32 v242, v242, v87
	v_add_f32_e32 v243, v243, v88
	v_add_f32_e32 v242, v242, v89
	v_exp_f32_e32 v90, v90
	v_exp_f32_e32 v91, v91
	ds_read_b64_tr_b16 v[214:215], v190 offset:9408
	ds_read_b64_tr_b16 v[216:217], v190 offset:11968
	s_waitcnt lgkmcnt(4)
	v_mfma_f32_32x32x16_bf16 v[50:65], v[82:85], v[244:247], v[50:65]
	v_exp_f32_e32 v92, v92
	v_exp_f32_e32 v93, v93
	v_exp_f32_e32 v94, v94
	ds_read_b64_tr_b16 v[244:245], v190 offset:14336
	ds_read_b64_tr_b16 v[246:247], v190 offset:16896
	s_waitcnt lgkmcnt(4)
	v_mfma_f32_32x32x16_bf16 v[34:49], v[82:85], v[206:209], v[34:49]
	v_exp_f32_e32 v95, v95
	v_exp_f32_e32 v96, v96
	v_exp_f32_e32 v97, v97
	v_add_f32_e32 v243, v243, v90
	ds_read_b64_tr_b16 v[206:207], v190 offset:14400
	ds_read_b64_tr_b16 v[208:209], v190 offset:16960
	s_waitcnt lgkmcnt(4)
	v_mfma_f32_32x32x16_bf16 v[18:33], v[82:85], v[214:217], v[18:33]
	v_add_f32_e32 v242, v242, v91
	v_add_f32_e32 v243, v243, v92
	v_add_f32_e32 v242, v242, v93
	v_cvt_pk_bf16_f32 v90, v90, v91
	v_cvt_pk_bf16_f32 v91, v92, v93
	v_cvt_pk_bf16_f32 v92, v94, v95
	v_cvt_pk_bf16_f32 v93, v96, v97
	s_nop 0
	ds_read_b64_tr_b16 v[214:215], v190 offset:14464
	ds_read_b64_tr_b16 v[216:217], v190 offset:17024
	s_waitcnt lgkmcnt(4)
	v_mfma_f32_32x32x16_bf16 v[2:17], v[90:93], v[244:247], v[2:17]
	v_add_f32_e32 v243, v243, v94
	v_add_f32_e32 v242, v242, v95
	v_add_f32_e32 v243, v243, v96
	v_add_f32_e32 v242, v242, v97
	v_exp_f32_e32 v98, v98
	v_exp_f32_e32 v99, v99
	ds_read_b64_tr_b16 v[244:245], v190 offset:14528
	ds_read_b64_tr_b16 v[246:247], v190 offset:17088
	s_waitcnt lgkmcnt(4)
	v_mfma_f32_32x32x16_bf16 v[50:65], v[90:93], v[206:209], v[50:65]
	v_exp_f32_e32 v100, v100
	v_exp_f32_e32 v101, v101
	v_exp_f32_e32 v102, v102
	ds_read_b64_tr_b16 v[206:207], v190 offset:19456
	ds_read_b64_tr_b16 v[208:209], v190 offset:22016
	s_waitcnt lgkmcnt(4)
	v_mfma_f32_32x32x16_bf16 v[34:49], v[90:93], v[214:217], v[34:49]
	v_exp_f32_e32 v103, v103
	v_exp_f32_e32 v104, v104
	v_exp_f32_e32 v105, v105
	v_add_f32_e32 v243, v243, v98
	ds_read_b64_tr_b16 v[214:215], v190 offset:19520
	ds_read_b64_tr_b16 v[216:217], v190 offset:22080
	s_waitcnt lgkmcnt(4)
	v_mfma_f32_32x32x16_bf16 v[18:33], v[90:93], v[244:247], v[18:33]
	v_add_f32_e32 v242, v242, v99
	v_add_f32_e32 v243, v243, v100
	v_add_f32_e32 v242, v242, v101
	v_cvt_pk_bf16_f32 v98, v98, v99
	v_cvt_pk_bf16_f32 v99, v100, v101
	v_cvt_pk_bf16_f32 v100, v102, v103
	v_cvt_pk_bf16_f32 v101, v104, v105
	s_nop 0
	ds_read_b64_tr_b16 v[244:245], v190 offset:19584
	ds_read_b64_tr_b16 v[246:247], v190 offset:22144
	s_waitcnt lgkmcnt(4)
	v_mfma_f32_32x32x16_bf16 v[2:17], v[98:101], v[206:209], v[2:17]
	v_add_f32_e32 v243, v243, v102
	v_add_f32_e32 v242, v242, v103
	v_add_f32_e32 v243, v243, v104
	v_add_f32_e32 v242, v242, v105
	v_exp_f32_e32 v106, v106
	v_exp_f32_e32 v107, v107
	ds_read_b64_tr_b16 v[206:207], v190 offset:19648
	ds_read_b64_tr_b16 v[208:209], v190 offset:22208
	s_waitcnt lgkmcnt(4)
	v_mfma_f32_32x32x16_bf16 v[50:65], v[98:101], v[214:217], v[50:65]
	v_exp_f32_e32 v108, v108
	v_exp_f32_e32 v109, v109
	v_exp_f32_e32 v110, v110
	ds_read_b64_tr_b16 v[214:215], v190 offset:24576
	ds_read_b64_tr_b16 v[216:217], v190 offset:27136
	s_waitcnt lgkmcnt(4)
	v_mfma_f32_32x32x16_bf16 v[34:49], v[98:101], v[244:247], v[34:49]
	v_exp_f32_e32 v111, v111
	v_exp_f32_e32 v112, v112
	v_exp_f32_e32 v113, v113
	v_add_f32_e32 v243, v243, v106
	ds_read_b64_tr_b16 v[244:245], v190 offset:24640
	ds_read_b64_tr_b16 v[246:247], v190 offset:27200
	s_waitcnt lgkmcnt(4)
	v_mfma_f32_32x32x16_bf16 v[18:33], v[98:101], v[206:209], v[18:33]
	v_add_f32_e32 v242, v242, v107
	v_add_f32_e32 v243, v243, v108
	v_add_f32_e32 v242, v242, v109
	v_cvt_pk_bf16_f32 v106, v106, v107
	v_cvt_pk_bf16_f32 v107, v108, v109
	v_cvt_pk_bf16_f32 v108, v110, v111
	v_cvt_pk_bf16_f32 v109, v112, v113
	s_nop 0
	ds_read_b64_tr_b16 v[206:207], v190 offset:24704
	ds_read_b64_tr_b16 v[208:209], v190 offset:27264
	s_waitcnt lgkmcnt(4)
	v_mfma_f32_32x32x16_bf16 v[2:17], v[106:109], v[214:217], v[2:17]
	v_add_f32_e32 v243, v243, v110
	v_add_f32_e32 v242, v242, v111
	v_add_f32_e32 v243, v243, v112
	v_add_f32_e32 v242, v242, v113
	v_add_f32_e32 v243, v243, v242
	ds_read_b64_tr_b16 v[214:215], v190 offset:24768
	ds_read_b64_tr_b16 v[216:217], v190 offset:27328
	s_waitcnt lgkmcnt(4)
	v_mfma_f32_32x32x16_bf16 v[50:65], v[106:109], v[244:247], v[50:65]
	s_waitcnt lgkmcnt(2)
	v_mfma_f32_32x32x16_bf16 v[34:49], v[106:109], v[206:209], v[34:49]
	s_waitcnt lgkmcnt(0)
	v_mfma_f32_32x32x16_bf16 v[18:33], v[106:109], v[214:217], v[18:33]
	s_setprio 0
	s_movk_i32 s77, 0x110
.LBB0_77:
	s_add_i32 s22, s22, 64
	s_mov_b64 s[28:29], 0x60000
	s_add_i32 s4, s4, 1
	v_lshl_add_u64 v[164:165], v[164:165], 0, s[28:29]
	v_lshl_add_u64 v[162:163], v[162:163], 0, s[28:29]
	s_cmp_lg_u32 s10, s22
	v_lshl_add_u64 v[160:161], v[160:161], 0, s[28:29]
	s_waitcnt lgkmcnt(0)
	s_barrier
	s_cbranch_scc0 .Lfo_out_c3
	s_cmp_lt_u32 s4, s5
	s_cselect_b64 s[28:29], -1, 0
	s_branch .LBB0_66

.LBB0_81:
	s_add_i32 s23, s22, -1
	s_and_b32 s23, s23, 1
	s_cmp_gt_u32 s4, s11
	s_cbranch_scc1 .LBB0_88
	s_mul_i32 s26, s23, 0x7400
	s_add_i32 s26, s26, 0
	s_add_i32 s30, s4, 63
	s_xor_b32 s78, s23, 1
	s_mulk_i32 s78, 0x7400
	s_cmp_le_u32 s30, s1
	v_add3_u32 v152, s26, v177, v178
	ds_read_b128 v[98:101], v152
	ds_read_b128 v[102:105], v152 offset:32
	ds_read_b128 v[106:109], v152 offset:64
	ds_read_b128 v[110:113], v152 offset:96
	ds_read_b128 v[154:157], v152 offset:4608
	ds_read_b128 v[162:165], v152 offset:4640
	ds_read_b128 v[190:193], v152 offset:4672
	ds_read_b128 v[206:209], v152 offset:4704
	s_setprio 1
	s_waitcnt lgkmcnt(7)
	v_mfma_f32_32x32x16_bf16 v[82:97], v[98:101], v[118:121], v[66:81]
	s_waitcnt lgkmcnt(6)
	v_mfma_f32_32x32x16_bf16 v[82:97], v[102:105], v[122:125], v[82:97]
	s_waitcnt lgkmcnt(5)
	v_mfma_f32_32x32x16_bf16 v[82:97], v[106:109], v[126:129], v[82:97]
	s_waitcnt lgkmcnt(4)
	v_mfma_f32_32x32x16_bf16 v[82:97], v[110:113], v[134:137], v[82:97]
	v_add3_u32 v166, s78, v174, v0
	v_add_u32_e32 v167, s78, v144
	v_add_u32_e32 v168, v167, v175
	v_add_u32_e32 v167, v167, v176
	s_waitcnt vmcnt(2)
	ds_write_b128 v166, v[114:117]
	s_waitcnt vmcnt(1)
	ds_write_b128 v168, v[130:133] offset:9216
	s_waitcnt vmcnt(0)
	ds_write_b128 v167, v[138:141] offset:9216
	s_waitcnt lgkmcnt(6)
	v_mfma_f32_32x32x16_bf16 v[98:113], v[154:157], v[118:121], v[66:81]
	s_waitcnt lgkmcnt(5)
	v_mfma_f32_32x32x16_bf16 v[98:113], v[162:165], v[122:125], v[98:113]
	s_waitcnt lgkmcnt(4)
	v_mfma_f32_32x32x16_bf16 v[98:113], v[190:193], v[126:129], v[98:113]
	s_waitcnt lgkmcnt(3)
	v_mfma_f32_32x32x16_bf16 v[98:113], v[206:209], v[134:137], v[98:113]
	s_setprio 0
	s_cbranch_scc1 .LBB0_84
	v_add_u32_e32 v152, s4, v179
	v_cmp_le_i32_e32 vcc, v152, v183
	v_add_u32_e32 v154, 2, v152
	s_nop 7
	v_cndmask_b32_e32 v98, v220, v98, vcc
	v_cmp_lt_i32_e32 vcc, v152, v173
	s_nop 1
	v_cndmask_b32_e32 v83, v220, v83, vcc
	v_cmp_le_i32_e32 vcc, v152, v173
	s_nop 1
	v_cndmask_b32_e32 v82, v220, v82, vcc
	v_cmp_le_i32_e32 vcc, v152, v184
	s_nop 1
	v_cndmask_b32_e32 v99, v220, v99, vcc
	v_cmp_le_i32_e32 vcc, v154, v173
	v_add_u32_e32 v154, 3, v152
	s_nop 0
	v_cndmask_b32_e32 v84, v220, v84, vcc
	v_cmp_le_i32_e32 vcc, v152, v185
	s_nop 1
	v_cndmask_b32_e32 v100, v220, v100, vcc
	v_cmp_le_i32_e32 vcc, v154, v173
	s_nop 1
	v_cndmask_b32_e32 v85, v220, v85, vcc
	v_cmp_le_i32_e32 vcc, v152, v186
	s_nop 1
	v_cndmask_b32_e32 v101, v220, v101, vcc
	v_cmp_le_i32_e32 vcc, v152, v187
	s_nop 1
	v_cndmask_b32_e32 v86, v220, v86, vcc
	v_cmp_le_i32_e32 vcc, v152, v188
	s_nop 1
	v_cndmask_b32_e32 v102, v220, v102, vcc
	v_cmp_le_i32_e32 vcc, v152, v189
	s_nop 1
	v_cndmask_b32_e32 v87, v220, v87, vcc
	v_cmp_le_i32_e32 vcc, v152, v195
	s_nop 1
	v_cndmask_b32_e32 v103, v220, v103, vcc
	v_cmp_le_i32_e32 vcc, v152, v196
	s_nop 1
	v_cndmask_b32_e32 v88, v220, v88, vcc
	v_cmp_le_i32_e32 vcc, v152, v197
	s_nop 1
	v_cndmask_b32_e32 v104, v220, v104, vcc
	v_cmp_le_i32_e32 vcc, v152, v198
	s_nop 1
	v_cndmask_b32_e32 v89, v220, v89, vcc
	v_cmp_le_i32_e32 vcc, v152, v199
	s_nop 1
	v_cndmask_b32_e32 v105, v220, v105, vcc
	v_cmp_le_i32_e32 vcc, v152, v200
	s_nop 1
	v_cndmask_b32_e32 v90, v220, v90, vcc
	v_cmp_le_i32_e32 vcc, v152, v201
	s_nop 1
	v_cndmask_b32_e32 v106, v220, v106, vcc
	v_cmp_le_i32_e32 vcc, v152, v202
	s_nop 1
	v_cndmask_b32_e32 v91, v220, v91, vcc
	v_cmp_le_i32_e32 vcc, v152, v203
	s_nop 1
	v_cndmask_b32_e32 v107, v220, v107, vcc
	v_cmp_le_i32_e32 vcc, v152, v204
	s_nop 1
	v_cndmask_b32_e32 v92, v220, v92, vcc
	v_cmp_le_i32_e32 vcc, v152, v205
	s_nop 1
	v_cndmask_b32_e32 v108, v220, v108, vcc
	v_cmp_le_i32_e32 vcc, v152, v228
	s_nop 1
	v_cndmask_b32_e32 v93, v220, v93, vcc
	v_cmp_le_i32_e32 vcc, v152, v229
	s_nop 1
	v_cndmask_b32_e32 v109, v220, v109, vcc
	v_cmp_le_i32_e32 vcc, v152, v230
	s_nop 1
	v_cndmask_b32_e32 v94, v220, v94, vcc
	v_cmp_le_i32_e32 vcc, v152, v231
	s_nop 1
	v_cndmask_b32_e32 v110, v220, v110, vcc
	v_cmp_le_i32_e32 vcc, v152, v232
	s_nop 1
	v_cndmask_b32_e32 v95, v220, v95, vcc
	v_cmp_le_i32_e32 vcc, v152, v233
	s_nop 1
	v_cndmask_b32_e32 v111, v220, v111, vcc
	v_cmp_le_i32_e32 vcc, v152, v234
	s_nop 1
	v_cndmask_b32_e32 v96, v220, v96, vcc
	v_cmp_le_i32_e32 vcc, v152, v235
	s_nop 1
	v_cndmask_b32_e32 v112, v220, v112, vcc
	v_cmp_le_i32_e32 vcc, v152, v236
	s_nop 1
	v_cndmask_b32_e32 v97, v220, v97, vcc
	v_cmp_le_i32_e32 vcc, v152, v237
	s_nop 1
	v_cndmask_b32_e32 v113, v220, v113, vcc
.LBB0_84:
	s_add_i32 s78, s22, 1
	s_cmp_lt_u32 s78, s5
	s_cbranch_scc0 .Lw_no_c4m
	s_mov_b32 s98, 0x60000
	s_mov_b32 s99, 0
	v_lshl_add_u64 v[154:155], v[150:151], 0, s[36:37]
	v_lshl_add_u64 v[154:155], v[154:155], 0, s[98:99]
	global_load_dwordx4 v[114:117], v[154:155], off
	v_lshl_add_u64 v[156:157], v[148:149], 0, s[36:37]
	v_lshl_add_u64 v[156:157], v[156:157], 0, s[98:99]
	global_load_dwordx4 v[130:133], v[156:157], off
	v_lshl_add_u64 v[154:155], v[146:147], 0, s[36:37]
	v_lshl_add_u64 v[154:155], v[154:155], 0, s[98:99]
	global_load_dwordx4 v[138:141], v[154:155], off
	s_nop 1
	s_branch .Lw_go_c4

.LBB0_88:
	s_xor_b32 s78, s23, 1
	s_mulk_i32 s78, 0x7400
	v_add3_u32 v82, s78, v174, v0
	v_add_u32_e32 v83, s78, v144
	v_add_u32_e32 v84, v83, v175
	v_add_u32_e32 v83, v83, v176
	s_waitcnt vmcnt(2)
	ds_write_b128 v82, v[114:117]
	s_waitcnt vmcnt(1)
	ds_write_b128 v84, v[130:133] offset:9216
	s_waitcnt vmcnt(0)
	ds_write_b128 v83, v[138:141] offset:9216
	s_add_i32 s78, s22, 1
	s_cmp_lt_u32 s78, s5
	s_cbranch_scc0 .Lw_no_c4s
	s_mov_b32 s98, 0x60000
	s_mov_b32 s99, 0
	v_lshl_add_u64 v[154:155], v[150:151], 0, s[36:37]
	v_lshl_add_u64 v[154:155], v[154:155], 0, s[98:99]
	global_load_dwordx4 v[114:117], v[154:155], off
	v_lshl_add_u64 v[156:157], v[148:149], 0, s[36:37]
	v_lshl_add_u64 v[156:157], v[156:157], 0, s[98:99]
	global_load_dwordx4 v[130:133], v[156:157], off
	v_lshl_add_u64 v[154:155], v[146:147], 0, s[36:37]
	v_lshl_add_u64 v[154:155], v[154:155], 0, s[98:99]
	global_load_dwordx4 v[138:141], v[154:155], off
.Lw_no_c4s:
	s_branch .LBB0_92
.LBB0_89:
.LBB0_90:
	v_add3_u32 v153, s26, v182, v181
	ds_read_b64_tr_b16 v[154:155], v153 offset:9216
	ds_read_b64_tr_b16 v[156:157], v153 offset:11776
	ds_read_b64_tr_b16 v[162:163], v153 offset:9280
	ds_read_b64_tr_b16 v[164:165], v153 offset:11840
	ds_read_b64_tr_b16 v[190:191], v153 offset:9344
	ds_read_b64_tr_b16 v[192:193], v153 offset:11904
	ds_read_b64_tr_b16 v[206:207], v153 offset:9408
	ds_read_b64_tr_b16 v[208:209], v153 offset:11968
	v_exp_f32_e32 v82, v82
	v_exp_f32_e32 v83, v83
	v_exp_f32_e32 v84, v84
	v_exp_f32_e32 v85, v85
	v_exp_f32_e32 v86, v86
	v_exp_f32_e32 v87, v87
	v_exp_f32_e32 v88, v88
	v_exp_f32_e32 v89, v89
	v_add_f32_e32 v239, v82, v83
	v_add_f32_e32 v238, v238, v84
	v_add_f32_e32 v239, v239, v85
	v_cvt_pk_bf16_f32 v82, v82, v83
	v_cvt_pk_bf16_f32 v83, v84, v85
	v_cvt_pk_bf16_f32 v84, v86, v87
	v_cvt_pk_bf16_f32 v85, v88, v89
	s_setprio 1
	s_waitcnt lgkmcnt(6)
	v_mfma_f32_32x32x16_bf16 v[2:17], v[82:85], v[154:157], v[2:17]
	v_add_f32_e32 v238, v238, v86
	v_add_f32_e32 v239, v239, v87
	v_add_f32_e32 v238, v238, v88
	v_add_f32_e32 v239, v239, v89
	v_exp_f32_e32 v90, v90
	v_exp_f32_e32 v91, v91
	ds_read_b64_tr_b16 v[154:155], v153 offset:14336
	ds_read_b64_tr_b16 v[156:157], v153 offset:16896
	s_waitcnt lgkmcnt(6)
	v_mfma_f32_32x32x16_bf16 v[50:65], v[82:85], v[162:165], v[50:65]
	v_exp_f32_e32 v92, v92
	v_exp_f32_e32 v93, v93
	v_exp_f32_e32 v94, v94
	ds_read_b64_tr_b16 v[162:163], v153 offset:14400
	ds_read_b64_tr_b16 v[164:165], v153 offset:16960
	s_waitcnt lgkmcnt(6)
	v_mfma_f32_32x32x16_bf16 v[18:33], v[82:85], v[190:193], v[18:33]
	v_exp_f32_e32 v95, v95
	v_exp_f32_e32 v96, v96
	v_exp_f32_e32 v97, v97
	v_add_f32_e32 v238, v238, v90
	ds_read_b64_tr_b16 v[190:191], v153 offset:14464
	ds_read_b64_tr_b16 v[192:193], v153 offset:17024
	s_waitcnt lgkmcnt(6)
	v_mfma_f32_32x32x16_bf16 v[34:49], v[82:85], v[206:209], v[34:49]
	v_add_f32_e32 v239, v239, v91
	v_add_f32_e32 v238, v238, v92
	v_add_f32_e32 v239, v239, v93
	v_cvt_pk_bf16_f32 v90, v90, v91
	v_cvt_pk_bf16_f32 v91, v92, v93
	v_cvt_pk_bf16_f32 v92, v94, v95
	v_cvt_pk_bf16_f32 v93, v96, v97
	s_nop 0
	ds_read_b64_tr_b16 v[206:207], v153 offset:14528
	ds_read_b64_tr_b16 v[208:209], v153 offset:17088
	s_waitcnt lgkmcnt(6)
	v_mfma_f32_32x32x16_bf16 v[2:17], v[90:93], v[154:157], v[2:17]
	v_add_f32_e32 v238, v238, v94
	v_add_f32_e32 v239, v239, v95
	v_add_f32_e32 v238, v238, v96
	v_add_f32_e32 v239, v239, v97
	v_exp_f32_e32 v98, v98
	v_exp_f32_e32 v99, v99
	ds_read_b64_tr_b16 v[154:155], v153 offset:19456
	ds_read_b64_tr_b16 v[156:157], v153 offset:22016
	s_waitcnt lgkmcnt(6)
	v_mfma_f32_32x32x16_bf16 v[50:65], v[90:93], v[162:165], v[50:65]
	v_exp_f32_e32 v100, v100
	v_exp_f32_e32 v101, v101
	v_exp_f32_e32 v102, v102
	ds_read_b64_tr_b16 v[162:163], v153 offset:19520
	ds_read_b64_tr_b16 v[164:165], v153 offset:22080
	s_waitcnt lgkmcnt(6)
	v_mfma_f32_32x32x16_bf16 v[18:33], v[90:93], v[190:193], v[18:33]
	v_exp_f32_e32 v103, v103
	v_exp_f32_e32 v104, v104
	v_exp_f32_e32 v105, v105
	v_add_f32_e32 v238, v238, v98
	ds_read_b64_tr_b16 v[190:191], v153 offset:19584
	ds_read_b64_tr_b16 v[192:193], v153 offset:22144
	s_waitcnt lgkmcnt(6)
	v_mfma_f32_32x32x16_bf16 v[34:49], v[90:93], v[206:209], v[34:49]
	v_add_f32_e32 v239, v239, v99
	v_add_f32_e32 v238, v238, v100
	v_add_f32_e32 v239, v239, v101
	v_cvt_pk_bf16_f32 v98, v98, v99
	v_cvt_pk_bf16_f32 v99, v100, v101
	v_cvt_pk_bf16_f32 v100, v102, v103
	v_cvt_pk_bf16_f32 v101, v104, v105
	s_nop 0
	ds_read_b64_tr_b16 v[206:207], v153 offset:19648
	ds_read_b64_tr_b16 v[208:209], v153 offset:22208
	s_waitcnt lgkmcnt(6)
	v_mfma_f32_32x32x16_bf16 v[2:17], v[98:101], v[154:157], v[2:17]
	v_add_f32_e32 v238, v238, v102
	v_add_f32_e32 v239, v239, v103
	v_add_f32_e32 v238, v238, v104
	v_add_f32_e32 v239, v239, v105
	v_exp_f32_e32 v106, v106
	v_exp_f32_e32 v107, v107
	ds_read_b64_tr_b16 v[154:155], v153 offset:24576
	ds_read_b64_tr_b16 v[156:157], v153 offset:27136
	s_waitcnt lgkmcnt(6)
	v_mfma_f32_32x32x16_bf16 v[50:65], v[98:101], v[162:165], v[50:65]
	v_exp_f32_e32 v108, v108
	v_exp_f32_e32 v109, v109
	v_exp_f32_e32 v110, v110
	ds_read_b64_tr_b16 v[162:163], v153 offset:24640
	ds_read_b64_tr_b16 v[164:165], v153 offset:27200
	s_waitcnt lgkmcnt(6)
	v_mfma_f32_32x32x16_bf16 v[18:33], v[98:101], v[190:193], v[18:33]
	v_exp_f32_e32 v111, v111
	v_exp_f32_e32 v112, v112
	v_exp_f32_e32 v113, v113
	v_add_f32_e32 v238, v238, v106
	ds_read_b64_tr_b16 v[190:191], v153 offset:24704
	ds_read_b64_tr_b16 v[192:193], v153 offset:27264
	s_waitcnt lgkmcnt(6)
	v_mfma_f32_32x32x16_bf16 v[34:49], v[98:101], v[206:209], v[34:49]
	v_add_f32_e32 v239, v239, v107
	v_add_f32_e32 v238, v238, v108
	v_add_f32_e32 v239, v239, v109
	v_cvt_pk_bf16_f32 v106, v106, v107
	v_cvt_pk_bf16_f32 v107, v108, v109
	v_cvt_pk_bf16_f32 v108, v110, v111
	v_cvt_pk_bf16_f32 v109, v112, v113
	s_nop 0
	ds_read_b64_tr_b16 v[206:207], v153 offset:24768
	ds_read_b64_tr_b16 v[208:209], v153 offset:27328
	s_waitcnt lgkmcnt(6)
	v_mfma_f32_32x32x16_bf16 v[2:17], v[106:109], v[154:157], v[2:17]
	v_add_f32_e32 v238, v238, v110
	v_add_f32_e32 v239, v239, v111
	v_add_f32_e32 v238, v238, v112
	v_add_f32_e32 v239, v239, v113
	v_add_f32_e32 v238, v238, v239
	s_waitcnt lgkmcnt(4)
	v_mfma_f32_32x32x16_bf16 v[50:65], v[106:109], v[162:165], v[50:65]
	s_waitcnt lgkmcnt(2)
	v_mfma_f32_32x32x16_bf16 v[18:33], v[106:109], v[190:193], v[18:33]
	s_waitcnt lgkmcnt(0)
	v_mfma_f32_32x32x16_bf16 v[34:49], v[106:109], v[206:209], v[34:49]
	s_setprio 0
	s_movk_i32 s77, 0x110
.LBB0_92:
	s_add_i32 s4, s4, 64
	s_mov_b64 s[28:29], 0x60000
	s_add_i32 s22, s22, 1
	v_lshl_add_u64 v[146:147], v[146:147], 0, s[28:29]
	v_lshl_add_u64 v[148:149], v[148:149], 0, s[28:29]
	s_cmp_lg_u32 s10, s4
	v_lshl_add_u64 v[150:151], v[150:151], 0, s[28:29]
	s_waitcnt lgkmcnt(0)
	s_barrier
	s_cbranch_scc0 .Lfo_out_c4
	s_cmp_lt_u32 s22, s5
	s_cselect_b64 s[28:29], -1, 0
	s_branch .LBB0_81
